# even attention: last 8 MLA sample items per XCD queue split over keys into 6 parts (partials in dead workspace, last part merges in fixed order)
# baseline (speedup 1.0000x reference)
.Lxq_fetch:
	s_lshl_b32 s8, s80, 2
	v_mov_b32_e32 v2, 1
	v_mov_b32_e32 v5, s8
	s_waitcnt vmcnt(0)
	global_atomic_add v2, v5, v2, s[6:7] sc0
	s_waitcnt vmcnt(0)
	v_readfirstlane_b32 s8, v2
	s_cmpk_lt_u32 s8, 0x10c
	s_cbranch_scc1 .Lxq_got
	s_add_u32 s81, s81, 1
	s_add_u32 s80, s80, 1
	s_and_b32 s80, s80, 7
	s_cmp_lt_u32 s81, 8
	s_cbranch_scc1 .Lxq_fetch
	s_mov_b32 s81, 8
	s_movk_i32 s8, 0x720
	s_branch .Lxq_put

.Lxq_m1:
	s_cmpk_lt_u32 s8, 0x7c
	s_cbranch_scc0 .Lxq_m2
	s_lshl_b32 s9, s80, 7
	s_add_u32 s8, s8, s9
	s_add_u32 s8, s8, 28
	s_branch .Lxq_put
.Lxq_m2:
	s_cmpk_lt_u32 s8, 0xac
	s_cbranch_scc0 .Lxq_m3
	s_sub_u32 s9, s8, 0x7c
	s_mul_i32 s10, s9, 43
	s_lshr_b32 s10, s10, 8
	s_mul_i32 s20, s10, 6
	s_sub_u32 s9, s9, s20
	s_add_u32 s9, s9, 1
	s_lshl_b32 s9, s9, 16
	s_lshl_b32 s8, s80, 7
	s_add_u32 s8, s8, s10
	s_addk_i32 s8, 0x98
	s_or_b32 s8, s8, s9
	s_branch .Lxq_put
.Lxq_m3:
	s_cmpk_lt_u32 s8, 0xcc
	s_cbranch_scc0 .Lxq_m4
	s_lshl_b32 s9, s80, 5
	s_add_u32 s8, s8, s9
	s_addk_i32 s8, 0x374
	s_branch .Lxq_put
.Lxq_m4:
	s_lshl_b32 s9, s80, 6
	s_add_u32 s8, s8, s9
	s_addk_i32 s8, 0x454

.LBB0_1380:
	s_or_b64 exec, exec, s[0:1]
	v_mov_b32_e32 v0, s69
	s_waitcnt lgkmcnt(0)
	s_barrier
	ds_read_b32 v0, v0
	s_waitcnt lgkmcnt(0)
	v_readfirstlane_b32 s23, v0
	s_lshr_b32 s79, s23, 16
	s_and_b32 s23, s23, 0xffff
	s_cmpk_gt_i32 s23, 0x71f
	s_cbranch_scc1 .LBB0_1488
	s_cmp_gt_i32 s23, 31
	s_mov_b64 s[0:1], -1
	s_cbranch_scc0 .LBB0_1462
	s_cmpk_gt_u32 s23, 0x41f
	s_cbranch_scc0 .LBB0_1435
	s_cmpk_gt_u32 s23, 0x51f
	s_cbranch_scc0 .LBB0_1409
	s_mov_b64 s[0:1], 0
	s_add_u32 s13, s90, s0
	s_addc_u32 s46, s91, s1
	s_add_i32 s1, s23, 0xfffffae0
	s_lshl_b32 s0, s23, 7
	s_lshr_b32 s8, s1, 4
	s_lshl_b32 s1, s8, 8
	s_and_b32 s0, s0, 0x80
	s_or_b32 s38, s1, s0
	s_bfe_u32 s47, s23, 0x30001
	s_lshl_b64 s[0:1], s[38:39], 10
	s_lshl_b64 s[20:21], s[38:39], 11
	v_mov_b32_e32 v84, v179
	s_add_u32 s9, s13, s20
	s_movk_i32 s2, 0xffe0
	v_and_b32_e32 v85, 15, v84
	v_ashrrev_i32_e32 v0, 1, v84
	s_addc_u32 s10, s46, s21
	s_lshl_b32 s19, s47, 8
	s_waitcnt vmcnt(1)
	v_and_or_b32 v2, v0, s2, v85
	s_add_u32 s40, s9, s19
	v_bfe_u32 v86, v84, 4, 2
	v_ashrrev_i32_e32 v3, 31, v2
	s_addc_u32 s41, s10, 0
	v_lshlrev_b32_e32 v0, 4, v86
	v_lshlrev_b64 v[150:151], 11, v[2:3]
	v_or_b32_e32 v2, 16, v2
	v_lshl_add_u64 v[4:5], s[40:41], 0, v[0:1]
	s_mov_b64 s[2:3], 0x1733d700
	v_ashrrev_i32_e32 v3, 31, v2
	v_lshl_add_u64 v[20:21], v[4:5], 0, s[2:3]
	v_lshlrev_b64 v[148:149], 11, v[2:3]
	s_mov_b32 s9, s39
	v_lshl_add_u64 v[16:17], v[20:21], 0, v[150:151]
	v_lshl_add_u64 v[2:3], v[20:21], 0, v[148:149]
	v_mov_b32_e32 v52, v179
	s_lshl_b64 s[20:21], s[8:9], 19
	global_load_dwordx4 v[4:7], v[16:17], off
	global_load_dwordx4 v[8:11], v[16:17], off offset:64
	global_load_dwordx4 v[12:15], v[16:17], off offset:128
	s_nop 0
	global_load_dwordx4 v[16:19], v[16:17], off offset:192
	s_nop 0
	global_load_dwordx4 v[20:23], v[2:3], off
	global_load_dwordx4 v[24:27], v[2:3], off offset:64
	global_load_dwordx4 v[28:31], v[2:3], off offset:128
	global_load_dwordx4 v[32:35], v[2:3], off offset:192
	s_add_u32 s9, s13, s20
	v_ashrrev_i32_e32 v2, 31, v52
	v_lshrrev_b32_e32 v2, 28, v2
	s_addc_u32 s10, s46, s21
	v_add_u32_e32 v3, v52, v2
	s_add_u32 s9, s9, s19
	v_ashrrev_i32_e32 v2, 4, v3
	v_and_b32_e32 v3, 0x1ffffff0, v3
	s_addc_u32 s10, s10, 0
	v_sub_u32_e32 v3, v52, v3
	s_add_u32 s20, s9, 0x1c73d700
	v_lshlrev_b32_e32 v36, 3, v3
	v_ashrrev_i32_e32 v3, 31, v2
	s_addc_u32 s21, s10, 0
	v_lshlrev_b64 v[2:3], 11, v[2:3]
	v_lshl_add_u64 v[2:3], s[20:21], 0, v[2:3]
	v_ashrrev_i32_e32 v37, 31, v36
	v_add_u32_e32 v54, 0x100, v52
	v_lshl_add_u64 v[2:3], v[36:37], 1, v[2:3]
	v_ashrrev_i32_e32 v36, 31, v54
	v_lshrrev_b32_e32 v36, 28, v36
	v_add_u32_e32 v37, v54, v36
	v_ashrrev_i32_e32 v36, 4, v37
	v_and_b32_e32 v37, 0x1ffffff0, v37
	v_sub_u32_e32 v37, v54, v37
	v_lshlrev_b32_e32 v38, 3, v37
	v_ashrrev_i32_e32 v37, 31, v36
	v_lshlrev_b64 v[36:37], 11, v[36:37]
	v_lshl_add_u64 v[36:37], s[20:21], 0, v[36:37]
	v_ashrrev_i32_e32 v39, 31, v38
	v_lshl_add_u64 v[40:41], v[38:39], 1, v[36:37]
	global_load_dwordx4 v[36:39], v[2:3], off
	s_nop 0
	global_load_dwordx4 v[40:43], v[40:41], off
	v_add_u32_e32 v3, 0x200, v52
	v_ashrrev_i32_e32 v2, 31, v3
	v_lshrrev_b32_e32 v2, 28, v2
	v_add_u32_e32 v44, v3, v2
	v_ashrrev_i32_e32 v2, 4, v44
	v_and_b32_e32 v44, 0x1ffffff0, v44
	v_sub_u32_e32 v3, v3, v44
	v_lshlrev_b32_e32 v44, 3, v3
	v_ashrrev_i32_e32 v3, 31, v2
	v_lshlrev_b64 v[2:3], 11, v[2:3]
	v_lshl_add_u64 v[2:3], s[20:21], 0, v[2:3]
	v_ashrrev_i32_e32 v45, 31, v44
	v_lshl_add_u64 v[2:3], v[44:45], 1, v[2:3]
	v_add_u32_e32 v45, 0x300, v52
	v_ashrrev_i32_e32 v44, 31, v45
	v_lshrrev_b32_e32 v44, 28, v44
	v_add_u32_e32 v46, v45, v44
	v_ashrrev_i32_e32 v44, 4, v46
	v_and_b32_e32 v46, 0x1ffffff0, v46
	s_lshl_b32 s8, s8, 3
	v_sub_u32_e32 v45, v45, v46
	s_or_b32 s38, s8, s47
	v_lshlrev_b32_e32 v46, 3, v45
	v_ashrrev_i32_e32 v45, 31, v44
	s_lshl_b64 s[8:9], s[38:39], 15
	v_lshlrev_b64 v[44:45], 11, v[44:45]
	s_add_u32 s8, s13, s8
	v_lshl_add_u64 v[44:45], s[20:21], 0, v[44:45]
	v_ashrrev_i32_e32 v47, 31, v46
	s_addc_u32 s9, s46, s9
	v_lshl_add_u64 v[48:49], v[46:47], 1, v[44:45]
	s_add_u32 s34, s8, 0x1e93d700
	global_load_dwordx4 v[44:47], v[2:3], off
	s_nop 0
	global_load_dwordx4 v[48:51], v[48:49], off
	v_lshlrev_b32_e32 v2, 4, v52
	v_ashrrev_i32_e32 v52, 3, v52
	v_ashrrev_i32_e32 v54, 3, v54
	s_addc_u32 s35, s9, 0
	v_and_b32_e32 v2, 0x70, v2
	v_mov_b32_e32 v3, v1
	v_ashrrev_i32_e32 v53, 31, v52
	v_ashrrev_i32_e32 v55, 31, v54
	v_lshl_add_u64 v[2:3], s[34:35], 0, v[2:3]
	v_lshlrev_b64 v[52:53], 9, v[52:53]
	v_lshlrev_b64 v[54:55], 9, v[54:55]
	v_lshl_add_u64 v[52:53], v[2:3], 0, v[52:53]
	v_lshl_add_u64 v[2:3], v[2:3], 0, v[54:55]
	v_mov_b32_e32 v76, v179
	global_load_dwordx4 v[60:63], v[52:53], off
	global_load_dwordx4 v[64:67], v[2:3], off
	s_mov_b32 s2, 0x20000
	v_ashrrev_i32_e32 v2, 31, v76
	v_lshrrev_b32_e32 v2, 28, v2
	v_add_u32_e32 v3, v76, v2
	v_ashrrev_i32_e32 v2, 4, v3
	v_and_b32_e32 v3, 0x1ffffff0, v3
	v_sub_u32_e32 v3, v76, v3
	v_lshlrev_b32_e32 v52, 3, v3
	v_ashrrev_i32_e32 v3, 31, v2
	v_lshlrev_b64 v[2:3], 11, v[2:3]
	v_lshl_add_u64 v[2:3], s[20:21], 0, v[2:3]
	v_ashrrev_i32_e32 v53, 31, v52
	v_add_u32_e32 v78, 0x100, v76
	v_lshl_add_u64 v[2:3], v[52:53], 1, v[2:3]
	v_ashrrev_i32_e32 v52, 31, v78
	v_lshrrev_b32_e32 v52, 28, v52
	v_add_u32_e32 v53, v78, v52
	v_ashrrev_i32_e32 v52, 4, v53
	v_and_b32_e32 v53, 0x1ffffff0, v53
	v_sub_u32_e32 v53, v78, v53
	v_lshlrev_b32_e32 v54, 3, v53
	v_ashrrev_i32_e32 v53, 31, v52
	v_lshlrev_b64 v[52:53], 11, v[52:53]
	v_add_co_u32_e32 v2, vcc, s2, v2
	v_lshl_add_u64 v[52:53], s[20:21], 0, v[52:53]
	v_ashrrev_i32_e32 v55, 31, v54
	v_addc_co_u32_e32 v3, vcc, 0, v3, vcc
	v_lshl_add_u64 v[52:53], v[54:55], 1, v[52:53]
	v_add_co_u32_e32 v56, vcc, s2, v52
	v_ashrrev_i32_e32 v78, 3, v78
	s_nop 0
	v_addc_co_u32_e32 v57, vcc, 0, v53, vcc
	global_load_dwordx4 v[52:55], v[2:3], off
	s_nop 0
	global_load_dwordx4 v[56:59], v[56:57], off
	v_add_u32_e32 v3, 0x200, v76
	v_ashrrev_i32_e32 v2, 31, v3
	v_lshrrev_b32_e32 v2, 28, v2
	v_add_u32_e32 v68, v3, v2
	v_ashrrev_i32_e32 v2, 4, v68
	v_and_b32_e32 v68, 0x1ffffff0, v68
	v_sub_u32_e32 v3, v3, v68
	v_lshlrev_b32_e32 v68, 3, v3
	v_ashrrev_i32_e32 v3, 31, v2
	v_lshlrev_b64 v[2:3], 11, v[2:3]
	v_lshl_add_u64 v[2:3], s[20:21], 0, v[2:3]
	v_ashrrev_i32_e32 v69, 31, v68
	v_lshl_add_u64 v[2:3], v[68:69], 1, v[2:3]
	v_add_u32_e32 v69, 0x300, v76
	v_ashrrev_i32_e32 v68, 31, v69
	v_lshrrev_b32_e32 v68, 28, v68
	v_add_u32_e32 v70, v69, v68
	v_ashrrev_i32_e32 v68, 4, v70
	v_and_b32_e32 v70, 0x1ffffff0, v70
	v_sub_u32_e32 v69, v69, v70
	v_lshlrev_b32_e32 v70, 3, v69
	v_ashrrev_i32_e32 v69, 31, v68
	v_lshlrev_b64 v[68:69], 11, v[68:69]
	v_add_co_u32_e32 v2, vcc, s2, v2
	v_lshl_add_u64 v[68:69], s[20:21], 0, v[68:69]
	v_ashrrev_i32_e32 v71, 31, v70
	v_addc_co_u32_e32 v3, vcc, 0, v3, vcc
	v_lshl_add_u64 v[68:69], v[70:71], 1, v[68:69]
	v_add_co_u32_e32 v72, vcc, s2, v68
	v_ashrrev_i32_e32 v79, 31, v78
	s_nop 0
	v_addc_co_u32_e32 v73, vcc, 0, v69, vcc
	global_load_dwordx4 v[68:71], v[2:3], off
	s_nop 0
	global_load_dwordx4 v[72:75], v[72:73], off
	v_lshlrev_b32_e32 v2, 4, v76
	v_ashrrev_i32_e32 v76, 3, v76
	v_and_b32_e32 v2, 0x70, v2
	v_mov_b32_e32 v3, v1
	v_ashrrev_i32_e32 v77, 31, v76
	v_lshl_add_u64 v[2:3], s[34:35], 0, v[2:3]
	v_lshlrev_b64 v[76:77], 9, v[76:77]
	v_lshl_add_u64 v[76:77], v[2:3], 0, v[76:77]
	v_lshlrev_b64 v[78:79], 9, v[78:79]
	v_lshl_add_u64 v[2:3], v[2:3], 0, v[78:79]
	global_load_dwordx4 v[76:79], v[76:77], off offset:128
	s_nop 0
	global_load_dwordx4 v[80:83], v[2:3], off offset:128
	v_ashrrev_i32_e32 v2, 31, v84
	v_lshrrev_b32_e32 v2, 28, v2
	v_add_u32_e32 v2, v84, v2
	v_lshrrev_b32_e32 v3, 4, v2
	v_and_b32_e32 v2, 0xffffff0, v2
	v_sub_u32_e32 v2, v84, v2
	s_movk_i32 s2, 0x110
	v_mul_lo_u32 v3, v3, s2
	v_lshlrev_b32_e32 v2, 4, v2
	v_add3_u32 v160, 0, v3, v2
	v_add_u32_e32 v3, 0x100, v84
	v_ashrrev_i32_e32 v2, 31, v3
	v_lshrrev_b32_e32 v2, 28, v2
	v_add_u32_e32 v2, v3, v2
	v_lshrrev_b32_e32 v88, 4, v2
	v_and_b32_e32 v2, 0xffffff0, v2
	v_sub_u32_e32 v2, v3, v2
	v_mul_lo_u32 v88, v88, s2
	v_lshlrev_b32_e32 v2, 4, v2
	v_add3_u32 v161, 0, v88, v2
	v_add_u32_e32 v2, 0x200, v84
	v_ashrrev_i32_e32 v88, 31, v2
	v_lshrrev_b32_e32 v88, 28, v88
	v_add_u32_e32 v88, v2, v88
	v_lshrrev_b32_e32 v89, 4, v88
	v_and_b32_e32 v88, 0xffffff0, v88
	v_sub_u32_e32 v2, v2, v88
	v_mul_lo_u32 v88, v89, s2
	v_lshlrev_b32_e32 v2, 4, v2
	v_add3_u32 v162, 0, v88, v2
	v_add_u32_e32 v2, 0x300, v84
	v_ashrrev_i32_e32 v88, 31, v2
	v_lshrrev_b32_e32 v88, 28, v88
	v_add_u32_e32 v88, v2, v88
	v_lshrrev_b32_e32 v89, 4, v88
	v_and_b32_e32 v88, 0xffffff0, v88
	v_sub_u32_e32 v2, v2, v88
	v_mul_lo_u32 v88, v89, s2
	v_lshlrev_b32_e32 v2, 4, v2
	v_add3_u32 v163, 0, v88, v2
	v_lshlrev_b32_e32 v2, 4, v84
	v_and_b32_e32 v2, 0x70, v2
	v_add_u32_e32 v2, 0, v2
	v_lshrrev_b32_e32 v84, 3, v84
	v_mad_u64_u32 v[152:153], s[8:9], v84, s16, v[2:3]
	v_lshrrev_b32_e32 v3, 3, v3
	v_mad_u64_u32 v[154:155], s[8:9], v3, s16, v[2:3]
	v_mul_u32_u24_e32 v2, 0x88, v85
	v_lshlrev_b32_e32 v2, 1, v2
	v_add3_u32 v155, 0, v0, v2
	v_mul_u32_u24_e32 v0, 0x48, v85
	v_lshlrev_b32_e32 v87, 3, v86
	v_lshlrev_b32_e32 v0, 1, v0
	v_mov_b32_e32 v2, v1
	v_mov_b32_e32 v3, v1
	v_lshlrev_b32_e32 v153, 2, v86
	v_add3_u32 v164, 0, v0, v87
	v_mov_b32_e32 v0, v1
	v_mov_b32_e32 v156, 0
	v_mov_b64_e32 v[86:87], v[2:3]
	v_mov_b64_e32 v[90:91], v[2:3]
	v_mov_b64_e32 v[94:95], v[2:3]
	v_mov_b64_e32 v[98:99], v[2:3]
	v_mov_b64_e32 v[102:103], v[2:3]
	v_mov_b64_e32 v[106:107], v[2:3]
	v_mov_b64_e32 v[110:111], v[2:3]
	v_mov_b64_e32 v[114:115], v[2:3]
	v_add_u32_e32 v165, 0x900, v164
	v_add_u32_e32 v166, 0x1200, v164
	v_add_u32_e32 v167, 0x1b00, v164
	s_mov_b64 s[44:45], -1
	s_waitcnt vmcnt(20)
	v_mov_b32_e32 v171, 0xf149f2ca
	v_mov_b32_e32 v170, 0xf149f2ca
	v_mov_b64_e32 v[84:85], v[0:1]
	v_mov_b64_e32 v[88:89], v[0:1]
	v_mov_b64_e32 v[92:93], v[0:1]
	v_mov_b64_e32 v[96:97], v[0:1]
	v_mov_b64_e32 v[100:101], v[0:1]
	v_mov_b64_e32 v[104:105], v[0:1]
	v_mov_b64_e32 v[108:109], v[0:1]
	v_mov_b64_e32 v[112:113], v[0:1]
	v_mov_b32_e32 v157, v156
	s_mov_b32 s2, 0x60000
	s_barrier
	s_waitcnt vmcnt(11)
	ds_write_b128 v160, v[36:39]
	s_waitcnt vmcnt(10)
	ds_write_b128 v161, v[40:43]
	s_waitcnt vmcnt(9)
	ds_write_b128 v162, v[44:47]
	s_waitcnt vmcnt(8)
	ds_write_b128 v163, v[48:51]
	s_waitcnt vmcnt(7)
	ds_write_b128 v152, v[60:63] offset:17408
	s_waitcnt vmcnt(6)
	ds_write_b128 v154, v[64:67] offset:17408
	s_waitcnt lgkmcnt(0)
	s_barrier
	s_branch .LBB0_1386

.LBB0_1435:
	s_andn2_b64 vcc, exec, s[0:1]
	s_cbranch_vccnz .LBB0_1461
	s_sub_i32 s0, s23, 32
	s_mov_b64 s[8:9], 0
	s_max_u32 s60, s79, 1
	s_sub_u32 s60, s60, 1
	s_mul_i32 s61, s60, 0x600
	s_mul_i32 s60, s60, 0x180000
	s_cmp_eq_u32 s79, 0
	s_cselect_b32 s63, 0, 60
	s_add_u32 s46, s90, s8
	s_addc_u32 s13, s91, s9
	s_bfe_u32 s19, s0, 0x30005
	s_lshr_b32 s28, s0, 8
	s_lshl_b32 s0, s0, 17
	s_and_b32 s0, s0, 0x3e0000
	s_lshl_b32 s1, s28, 22
	s_or_b32 s0, s1, s0
	s_add_i32 s38, s0, 0x800000
	s_lshl_b64 s[0:1], s[38:39], 1
	v_mov_b32_e32 v84, v179
	s_add_u32 s10, s46, s0
	s_movk_i32 s2, 0xffe0
	v_and_b32_e32 v85, 15, v84
	v_ashrrev_i32_e32 v0, 1, v84
	s_addc_u32 s20, s13, s1
	s_lshl_b32 s34, s19, 8
	s_waitcnt vmcnt(1)
	v_and_or_b32 v2, v0, s2, v85
	s_add_u32 s40, s10, s34
	v_bfe_u32 v86, v84, 4, 2
	v_ashrrev_i32_e32 v3, 31, v2
	s_addc_u32 s41, s20, 0
	v_lshlrev_b32_e32 v0, 4, v86
	v_lshlrev_b64 v[150:151], 11, v[2:3]
	v_or_b32_e32 v2, 16, v2
	v_lshl_add_u64 v[4:5], s[40:41], 0, v[0:1]
	s_mov_b64 s[2:3], 0x1733d700
	v_ashrrev_i32_e32 v3, 31, v2
	v_lshl_add_u64 v[20:21], v[4:5], 0, s[2:3]
	v_lshlrev_b64 v[148:149], 11, v[2:3]
	s_mul_i32 s38, s28, 0x480000
	v_lshl_add_u64 v[16:17], v[20:21], 0, v[150:151]
	v_lshl_add_u64 v[2:3], v[20:21], 0, v[148:149]
	v_mov_b32_e32 v52, v179
	s_lshl_b64 s[20:21], s[38:39], 1
	global_load_dwordx4 v[4:7], v[16:17], off
	global_load_dwordx4 v[8:11], v[16:17], off offset:64
	global_load_dwordx4 v[12:15], v[16:17], off offset:128
	s_nop 0
	global_load_dwordx4 v[16:19], v[16:17], off offset:192
	s_nop 0
	global_load_dwordx4 v[20:23], v[2:3], off
	global_load_dwordx4 v[24:27], v[2:3], off offset:64
	global_load_dwordx4 v[28:31], v[2:3], off offset:128
	global_load_dwordx4 v[32:35], v[2:3], off offset:192
	s_add_u32 s10, s46, s20
	v_ashrrev_i32_e32 v2, 31, v52
	v_lshrrev_b32_e32 v2, 28, v2
	s_addc_u32 s20, s13, s21
	v_add_u32_e32 v3, v52, v2
	s_add_u32 s10, s10, s34
	v_ashrrev_i32_e32 v2, 4, v3
	v_and_b32_e32 v3, 0x1ffffff0, v3
	s_addc_u32 s21, s20, 0
	v_sub_u32_e32 v3, v52, v3
	s_add_u32 s20, s10, 0x1a33d700
	v_lshlrev_b32_e32 v36, 3, v3
	v_ashrrev_i32_e32 v3, 31, v2
	s_addc_u32 s21, s21, 0
	s_add_u32 s20, s20, s60
	s_addc_u32 s21, s21, 0
	v_lshlrev_b64 v[2:3], 11, v[2:3]
	v_lshl_add_u64 v[2:3], s[20:21], 0, v[2:3]
	v_ashrrev_i32_e32 v37, 31, v36
	v_add_u32_e32 v54, 0x100, v52
	v_lshl_add_u64 v[2:3], v[36:37], 1, v[2:3]
	v_ashrrev_i32_e32 v36, 31, v54
	v_lshrrev_b32_e32 v36, 28, v36
	v_add_u32_e32 v37, v54, v36
	v_ashrrev_i32_e32 v36, 4, v37
	v_and_b32_e32 v37, 0x1ffffff0, v37
	v_sub_u32_e32 v37, v54, v37
	v_lshlrev_b32_e32 v38, 3, v37
	v_ashrrev_i32_e32 v37, 31, v36
	v_lshlrev_b64 v[36:37], 11, v[36:37]
	v_lshl_add_u64 v[36:37], s[20:21], 0, v[36:37]
	v_ashrrev_i32_e32 v39, 31, v38
	v_lshl_add_u64 v[40:41], v[38:39], 1, v[36:37]
	global_load_dwordx4 v[36:39], v[2:3], off
	s_nop 0
	global_load_dwordx4 v[40:43], v[40:41], off
	v_add_u32_e32 v3, 0x200, v52
	v_ashrrev_i32_e32 v2, 31, v3
	v_lshrrev_b32_e32 v2, 28, v2
	v_add_u32_e32 v44, v3, v2
	v_ashrrev_i32_e32 v2, 4, v44
	v_and_b32_e32 v44, 0x1ffffff0, v44
	v_sub_u32_e32 v3, v3, v44
	v_lshlrev_b32_e32 v44, 3, v3
	v_ashrrev_i32_e32 v3, 31, v2
	v_lshlrev_b64 v[2:3], 11, v[2:3]
	v_lshl_add_u64 v[2:3], s[20:21], 0, v[2:3]
	v_ashrrev_i32_e32 v45, 31, v44
	v_lshl_add_u64 v[2:3], v[44:45], 1, v[2:3]
	v_add_u32_e32 v45, 0x300, v52
	v_ashrrev_i32_e32 v44, 31, v45
	v_lshrrev_b32_e32 v44, 28, v44
	v_add_u32_e32 v46, v45, v44
	s_lshl_b32 s10, s28, 9
	s_lshl_b32 s47, s19, 6
	v_ashrrev_i32_e32 v44, 4, v46
	v_and_b32_e32 v46, 0x1ffffff0, v46
	s_or_b32 s10, s47, s10
	v_sub_u32_e32 v45, v45, v46
	s_mul_i32 s38, s10, 0x1200
	v_lshlrev_b32_e32 v46, 3, v45
	v_ashrrev_i32_e32 v45, 31, v44
	s_lshl_b64 s[34:35], s[38:39], 1
	v_lshlrev_b64 v[44:45], 11, v[44:45]
	s_add_u32 s10, s46, s34
	v_lshl_add_u64 v[44:45], s[20:21], 0, v[44:45]
	v_ashrrev_i32_e32 v47, 31, v46
	s_addc_u32 s35, s13, s35
	v_lshl_add_u64 v[48:49], v[46:47], 1, v[44:45]
	s_add_u32 s34, s10, 0x1d73d700
	global_load_dwordx4 v[44:47], v[2:3], off
	s_nop 0
	global_load_dwordx4 v[48:51], v[48:49], off
	v_lshlrev_b32_e32 v2, 4, v52
	s_addc_u32 s35, s35, 0
	s_add_u32 s34, s34, s61
	s_addc_u32 s35, s35, 0
	v_and_b32_e32 v2, 0x70, v2
	v_mov_b32_e32 v3, v1
	v_lshl_add_u64 v[2:3], s[34:35], 0, v[2:3]
	v_ashrrev_i32_e32 v52, 3, v52
	v_ashrrev_i32_e32 v54, 3, v54
	v_mad_i64_i32 v[52:53], s[40:41], v52, s15, v[2:3]
	v_mad_i64_i32 v[2:3], s[40:41], v54, s15, v[2:3]
	v_mov_b32_e32 v76, v179
	global_load_dwordx4 v[60:63], v[52:53], off
	global_load_dwordx4 v[64:67], v[2:3], off
	s_mov_b32 s2, 0x20000
	v_ashrrev_i32_e32 v2, 31, v76
	v_lshrrev_b32_e32 v2, 28, v2
	v_add_u32_e32 v3, v76, v2
	v_ashrrev_i32_e32 v2, 4, v3
	v_and_b32_e32 v3, 0x1ffffff0, v3
	v_sub_u32_e32 v3, v76, v3
	v_lshlrev_b32_e32 v52, 3, v3
	v_ashrrev_i32_e32 v3, 31, v2
	v_lshlrev_b64 v[2:3], 11, v[2:3]
	v_lshl_add_u64 v[2:3], s[20:21], 0, v[2:3]
	v_ashrrev_i32_e32 v53, 31, v52
	v_add_u32_e32 v78, 0x100, v76
	v_lshl_add_u64 v[2:3], v[52:53], 1, v[2:3]
	v_ashrrev_i32_e32 v52, 31, v78
	v_lshrrev_b32_e32 v52, 28, v52
	v_add_u32_e32 v53, v78, v52
	v_ashrrev_i32_e32 v52, 4, v53
	v_and_b32_e32 v53, 0x1ffffff0, v53
	v_sub_u32_e32 v53, v78, v53
	v_lshlrev_b32_e32 v54, 3, v53
	v_ashrrev_i32_e32 v53, 31, v52
	v_lshlrev_b64 v[52:53], 11, v[52:53]
	v_add_co_u32_e32 v2, vcc, s2, v2
	v_lshl_add_u64 v[52:53], s[20:21], 0, v[52:53]
	v_ashrrev_i32_e32 v55, 31, v54
	v_addc_co_u32_e32 v3, vcc, 0, v3, vcc
	v_lshl_add_u64 v[52:53], v[54:55], 1, v[52:53]
	v_add_co_u32_e32 v56, vcc, s2, v52
	v_ashrrev_i32_e32 v78, 3, v78
	s_nop 0
	v_addc_co_u32_e32 v57, vcc, 0, v53, vcc
	global_load_dwordx4 v[52:55], v[2:3], off
	s_nop 0
	global_load_dwordx4 v[56:59], v[56:57], off
	v_add_u32_e32 v3, 0x200, v76
	v_ashrrev_i32_e32 v2, 31, v3
	v_lshrrev_b32_e32 v2, 28, v2
	v_add_u32_e32 v68, v3, v2
	v_ashrrev_i32_e32 v2, 4, v68
	v_and_b32_e32 v68, 0x1ffffff0, v68
	v_sub_u32_e32 v3, v3, v68
	v_lshlrev_b32_e32 v68, 3, v3
	v_ashrrev_i32_e32 v3, 31, v2
	v_lshlrev_b64 v[2:3], 11, v[2:3]
	v_lshl_add_u64 v[2:3], s[20:21], 0, v[2:3]
	v_ashrrev_i32_e32 v69, 31, v68
	v_lshl_add_u64 v[2:3], v[68:69], 1, v[2:3]
	v_add_u32_e32 v69, 0x300, v76
	v_ashrrev_i32_e32 v68, 31, v69
	v_lshrrev_b32_e32 v68, 28, v68
	v_add_u32_e32 v70, v69, v68
	v_ashrrev_i32_e32 v68, 4, v70
	v_and_b32_e32 v70, 0x1ffffff0, v70
	v_sub_u32_e32 v69, v69, v70
	v_lshlrev_b32_e32 v70, 3, v69
	v_ashrrev_i32_e32 v69, 31, v68
	v_lshlrev_b64 v[68:69], 11, v[68:69]
	v_add_co_u32_e32 v2, vcc, s2, v2
	v_lshl_add_u64 v[68:69], s[20:21], 0, v[68:69]
	v_ashrrev_i32_e32 v71, 31, v70
	v_addc_co_u32_e32 v3, vcc, 0, v3, vcc
	v_lshl_add_u64 v[68:69], v[70:71], 1, v[68:69]
	v_add_co_u32_e32 v72, vcc, s2, v68
	s_movk_i32 s2, 0x110
	s_nop 0
	v_addc_co_u32_e32 v73, vcc, 0, v69, vcc
	global_load_dwordx4 v[68:71], v[2:3], off
	s_nop 0
	global_load_dwordx4 v[72:75], v[72:73], off
	v_lshlrev_b32_e32 v2, 4, v76
	v_and_b32_e32 v2, 0x70, v2
	v_mov_b32_e32 v3, v1
	v_lshl_add_u64 v[2:3], s[34:35], 0, v[2:3]
	v_ashrrev_i32_e32 v76, 3, v76
	v_mad_i64_i32 v[76:77], s[34:35], v76, s15, v[2:3]
	v_mad_i64_i32 v[2:3], s[34:35], v78, s15, v[2:3]
	global_load_dwordx4 v[76:79], v[76:77], off offset:128
	s_nop 0
	global_load_dwordx4 v[80:83], v[2:3], off offset:128
	v_ashrrev_i32_e32 v2, 31, v84
	v_lshrrev_b32_e32 v2, 28, v2
	v_add_u32_e32 v2, v84, v2
	v_lshrrev_b32_e32 v3, 4, v2
	v_and_b32_e32 v2, 0xffffff0, v2
	v_sub_u32_e32 v2, v84, v2
	v_mul_lo_u32 v3, v3, s2
	v_lshlrev_b32_e32 v2, 4, v2
	v_add3_u32 v160, 0, v3, v2
	v_add_u32_e32 v3, 0x100, v84
	v_ashrrev_i32_e32 v2, 31, v3
	v_lshrrev_b32_e32 v2, 28, v2
	v_add_u32_e32 v2, v3, v2
	v_lshrrev_b32_e32 v88, 4, v2
	v_and_b32_e32 v2, 0xffffff0, v2
	v_sub_u32_e32 v2, v3, v2
	v_mul_lo_u32 v88, v88, s2
	v_lshlrev_b32_e32 v2, 4, v2
	v_add3_u32 v161, 0, v88, v2
	v_add_u32_e32 v2, 0x200, v84
	v_ashrrev_i32_e32 v88, 31, v2
	v_lshrrev_b32_e32 v88, 28, v88
	v_add_u32_e32 v88, v2, v88
	v_lshrrev_b32_e32 v89, 4, v88
	v_and_b32_e32 v88, 0xffffff0, v88
	v_sub_u32_e32 v2, v2, v88
	v_mul_lo_u32 v88, v89, s2
	v_lshlrev_b32_e32 v2, 4, v2
	v_add3_u32 v162, 0, v88, v2
	v_add_u32_e32 v2, 0x300, v84
	v_ashrrev_i32_e32 v88, 31, v2
	v_lshrrev_b32_e32 v88, 28, v88
	v_add_u32_e32 v88, v2, v88
	v_lshrrev_b32_e32 v89, 4, v88
	v_and_b32_e32 v88, 0xffffff0, v88
	v_sub_u32_e32 v2, v2, v88
	v_mul_lo_u32 v88, v89, s2
	v_lshlrev_b32_e32 v2, 4, v2
	v_add3_u32 v163, 0, v88, v2
	v_lshlrev_b32_e32 v2, 4, v84
	v_and_b32_e32 v2, 0x70, v2
	v_add_u32_e32 v2, 0, v2
	v_lshrrev_b32_e32 v84, 3, v84
	v_mad_u64_u32 v[152:153], s[34:35], v84, s16, v[2:3]
	v_lshrrev_b32_e32 v3, 3, v3
	s_mul_i32 s28, s28, 0x240000
	s_mul_i32 s19, s19, 0x48000
	v_mad_u64_u32 v[154:155], s[34:35], v3, s16, v[2:3]
	v_mul_u32_u24_e32 v2, 0x88, v85
	s_add_i32 s38, s28, s19
	v_lshlrev_b32_e32 v2, 1, v2
	s_lshl_b64 s[34:35], s[38:39], 1
	v_add3_u32 v155, 0, v0, v2
	v_mul_u32_u24_e32 v0, 0x48, v85
	s_add_u32 s8, s8, s34
	v_lshlrev_b32_e32 v87, 3, v86
	v_lshlrev_b32_e32 v0, 1, v0
	s_addc_u32 s9, s9, s35
	v_readlane_b32 s2, v255, 4
	v_mov_b32_e32 v2, v1
	v_mov_b32_e32 v3, v1
	v_lshlrev_b32_e32 v153, 2, v86
	v_add3_u32 v164, 0, v0, v87
	s_add_u32 s34, s2, s8
	v_readlane_b32 s2, v255, 5
	v_mov_b32_e32 v0, v1
	v_mov_b32_e32 v156, 0
	v_mov_b64_e32 v[86:87], v[2:3]
	v_mov_b64_e32 v[90:91], v[2:3]
	v_mov_b64_e32 v[94:95], v[2:3]
	v_mov_b64_e32 v[98:99], v[2:3]
	v_mov_b64_e32 v[102:103], v[2:3]
	v_mov_b64_e32 v[106:107], v[2:3]
	v_mov_b64_e32 v[110:111], v[2:3]
	v_mov_b64_e32 v[114:115], v[2:3]
	s_mov_b32 s10, s63
	v_add_u32_e32 v165, 0x900, v164
	v_add_u32_e32 v166, 0x1200, v164
	v_add_u32_e32 v167, 0x1b00, v164
	s_movk_i32 s28, 0x1200
	s_addc_u32 s35, s2, s9
	s_add_u32 s34, s34, s61
	s_addc_u32 s35, s35, 0
	s_waitcnt vmcnt(20)
	v_mov_b32_e32 v171, 0xf149f2ca
	s_mov_b64 s[40:41], 0xc0
	v_mov_b32_e32 v170, 0xf149f2ca
	v_mov_b64_e32 v[84:85], v[0:1]
	v_mov_b64_e32 v[88:89], v[0:1]
	v_mov_b64_e32 v[92:93], v[0:1]
	v_mov_b64_e32 v[96:97], v[0:1]
	v_mov_b64_e32 v[100:101], v[0:1]
	v_mov_b64_e32 v[104:105], v[0:1]
	v_mov_b64_e32 v[108:109], v[0:1]
	v_mov_b64_e32 v[112:113], v[0:1]
	v_mov_b32_e32 v157, v156
	s_mov_b32 s2, 0xfffe0000
	s_barrier
	s_waitcnt vmcnt(11)
	ds_write_b128 v160, v[36:39]
	s_waitcnt vmcnt(10)
	ds_write_b128 v161, v[40:43]
	s_waitcnt vmcnt(9)
	ds_write_b128 v162, v[44:47]
	s_waitcnt vmcnt(8)
	ds_write_b128 v163, v[48:51]
	s_waitcnt vmcnt(7)
	ds_write_b128 v152, v[60:63] offset:17408
	s_waitcnt vmcnt(6)
	ds_write_b128 v154, v[64:67] offset:17408
	s_waitcnt lgkmcnt(0)
	s_barrier
	s_branch .LBB0_1438

.LBB0_1460:
	s_cmp_lg_u32 s79, 0
	s_cbranch_scc1 .Lsk_part

.Lsk_part:
	s_sub_u32 s50, s23, 32
	s_lshr_b32 s51, s50, 7
	s_and_b32 s52, s50, 0x7f
	s_sub_u32 s52, s52, 0x78
	s_sub_u32 s53, s79, 1
	s_lshl_b32 s54, s51, 3
	s_add_u32 s54, s54, s52
	s_mul_i32 s54, s54, 6
	s_mul_i32 s55, s54, 0x9000
	s_add_u32 s55, s55, 0x2813d700
	s_add_u32 s56, s90, s55
	s_addc_u32 s57, s91, 0
	s_mul_i32 s58, s53, 0x9000
	s_add_u32 s58, s56, s58
	s_addc_u32 s59, s57, 0
	v_lshlrev_b32_e32 v226, 4, v179
	v_mov_b32_e32 v228, v170
	v_mov_b32_e32 v229, v171
	v_mov_b32_e32 v230, v156
	v_mov_b32_e32 v231, v157
	global_store_dwordx4 v226, v[84:87], s[58:59]
	s_add_u32 s58, s58, 0x1000
	s_addc_u32 s59, s59, 0
	global_store_dwordx4 v226, v[88:91], s[58:59]
	s_add_u32 s58, s58, 0x1000
	s_addc_u32 s59, s59, 0
	global_store_dwordx4 v226, v[92:95], s[58:59]
	s_add_u32 s58, s58, 0x1000
	s_addc_u32 s59, s59, 0
	global_store_dwordx4 v226, v[96:99], s[58:59]
	s_add_u32 s58, s58, 0x1000
	s_addc_u32 s59, s59, 0
	global_store_dwordx4 v226, v[100:103], s[58:59]
	s_add_u32 s58, s58, 0x1000
	s_addc_u32 s59, s59, 0
	global_store_dwordx4 v226, v[104:107], s[58:59]
	s_add_u32 s58, s58, 0x1000
	s_addc_u32 s59, s59, 0
	global_store_dwordx4 v226, v[108:111], s[58:59]
	s_add_u32 s58, s58, 0x1000
	s_addc_u32 s59, s59, 0
	global_store_dwordx4 v226, v[112:115], s[58:59]
	s_add_u32 s58, s58, 0x1000
	s_addc_u32 s59, s59, 0
	global_store_dwordx4 v226, v[228:231], s[58:59]
	s_waitcnt vmcnt(0)
	s_barrier
	v_cmp_eq_u32_e32 vcc, 0, v179
	s_and_saveexec_b64 s[8:9], vcc
	s_cbranch_execz .Lsk_cnt_done
	buffer_wbl2 sc1
	s_and_b32 s5, s22, 16
	s_cmp_eq_u32 s5, 0
	s_cselect_b32 s5, 44, 14
	s_add_u32 s5, s5, s51
	s_lshl_b32 s5, s5, 2
	s_lshl_b32 s26, s52, 2
	s_lshl_b32 s32, 1, s26
	v_mov_b32_e32 v232, s5
	v_mov_b32_e32 v233, s32
	s_waitcnt vmcnt(0)
	global_atomic_add v233, v232, v233, s[90:91] sc0
	s_waitcnt vmcnt(0)
	v_lshrrev_b32_e32 v233, s26, v233
	v_and_b32_e32 v233, 15, v233
	v_mov_b32_e32 v232, s69
	ds_write_b32 v232, v233
.Lsk_cnt_done:
	s_or_b64 exec, exec, s[8:9]
	v_mov_b32_e32 v232, s69
	s_waitcnt lgkmcnt(0)
	s_barrier
	ds_read_b32 v232, v232
	s_waitcnt lgkmcnt(0)
	v_readfirstlane_b32 s5, v232
	s_cmp_eq_u32 s5, 5
	s_cbranch_scc0 .LBB0_1461
	buffer_inv sc1
	global_load_dwordx4 v[84:87], v226, s[56:57]
	s_add_u32 s56, s56, 0x1000
	s_addc_u32 s57, s57, 0
	global_load_dwordx4 v[88:91], v226, s[56:57]
	s_add_u32 s56, s56, 0x1000
	s_addc_u32 s57, s57, 0
	global_load_dwordx4 v[92:95], v226, s[56:57]
	s_add_u32 s56, s56, 0x1000
	s_addc_u32 s57, s57, 0
	global_load_dwordx4 v[96:99], v226, s[56:57]
	s_add_u32 s56, s56, 0x1000
	s_addc_u32 s57, s57, 0
	global_load_dwordx4 v[100:103], v226, s[56:57]
	s_add_u32 s56, s56, 0x1000
	s_addc_u32 s57, s57, 0
	global_load_dwordx4 v[104:107], v226, s[56:57]
	s_add_u32 s56, s56, 0x1000
	s_addc_u32 s57, s57, 0
	global_load_dwordx4 v[108:111], v226, s[56:57]
	s_add_u32 s56, s56, 0x1000
	s_addc_u32 s57, s57, 0
	global_load_dwordx4 v[112:115], v226, s[56:57]
	s_add_u32 s56, s56, 0x1000
	s_addc_u32 s57, s57, 0
	global_load_dwordx4 v[228:231], v226, s[56:57]
	s_add_u32 s56, s56, 0x1000
	s_addc_u32 s57, s57, 0
	s_waitcnt vmcnt(0)
	v_mov_b32_e32 v170, v228
	v_mov_b32_e32 v171, v229
	v_mov_b32_e32 v156, v230
	v_mov_b32_e32 v157, v231
	s_mov_b32 s5, 1
.Lsk_merge:
	global_load_dwordx4 v[52:55], v226, s[56:57]
	s_add_u32 s56, s56, 0x1000
	s_addc_u32 s57, s57, 0
	global_load_dwordx4 v[56:59], v226, s[56:57]
	s_add_u32 s56, s56, 0x1000
	s_addc_u32 s57, s57, 0
	global_load_dwordx4 v[60:63], v226, s[56:57]
	s_add_u32 s56, s56, 0x1000
	s_addc_u32 s57, s57, 0
	global_load_dwordx4 v[64:67], v226, s[56:57]
	s_add_u32 s56, s56, 0x1000
	s_addc_u32 s57, s57, 0
	global_load_dwordx4 v[68:71], v226, s[56:57]
	s_add_u32 s56, s56, 0x1000
	s_addc_u32 s57, s57, 0
	global_load_dwordx4 v[72:75], v226, s[56:57]
	s_add_u32 s56, s56, 0x1000
	s_addc_u32 s57, s57, 0
	global_load_dwordx4 v[76:79], v226, s[56:57]
	s_add_u32 s56, s56, 0x1000
	s_addc_u32 s57, s57, 0
	global_load_dwordx4 v[80:83], v226, s[56:57]
	s_add_u32 s56, s56, 0x1000
	s_addc_u32 s57, s57, 0
	global_load_dwordx4 v[228:231], v226, s[56:57]
	s_add_u32 s56, s56, 0x1000
	s_addc_u32 s57, s57, 0
	s_waitcnt vmcnt(0)
	v_max_f32_e32 v232, v170, v228
	v_sub_f32_e32 v233, v170, v232
	v_sub_f32_e32 v234, v228, v232
	v_exp_f32_e32 v233, v233
	v_exp_f32_e32 v234, v234
	s_nop 1
	v_mul_f32_e32 v156, v156, v233
	v_fmac_f32_e32 v156, v230, v234
	v_mul_f32_e32 v100, v100, v233
	v_fmac_f32_e32 v100, v68, v234
	v_mul_f32_e32 v101, v101, v233
	v_fmac_f32_e32 v101, v69, v234
	v_mul_f32_e32 v102, v102, v233
	v_fmac_f32_e32 v102, v70, v234
	v_mul_f32_e32 v103, v103, v233
	v_fmac_f32_e32 v103, v71, v234
	v_mul_f32_e32 v104, v104, v233
	v_fmac_f32_e32 v104, v72, v234
	v_mul_f32_e32 v105, v105, v233
	v_fmac_f32_e32 v105, v73, v234
	v_mul_f32_e32 v106, v106, v233
	v_fmac_f32_e32 v106, v74, v234
	v_mul_f32_e32 v107, v107, v233
	v_fmac_f32_e32 v107, v75, v234
	v_mul_f32_e32 v108, v108, v233
	v_fmac_f32_e32 v108, v76, v234
	v_mul_f32_e32 v109, v109, v233
	v_fmac_f32_e32 v109, v77, v234
	v_mul_f32_e32 v110, v110, v233
	v_fmac_f32_e32 v110, v78, v234
	v_mul_f32_e32 v111, v111, v233
	v_fmac_f32_e32 v111, v79, v234
	v_mul_f32_e32 v112, v112, v233
	v_fmac_f32_e32 v112, v80, v234
	v_mul_f32_e32 v113, v113, v233
	v_fmac_f32_e32 v113, v81, v234
	v_mul_f32_e32 v114, v114, v233
	v_fmac_f32_e32 v114, v82, v234
	v_mul_f32_e32 v115, v115, v233
	v_fmac_f32_e32 v115, v83, v234
	v_mov_b32_e32 v170, v232
	v_max_f32_e32 v232, v171, v229
	v_sub_f32_e32 v233, v171, v232
	v_sub_f32_e32 v234, v229, v232
	v_exp_f32_e32 v233, v233
	v_exp_f32_e32 v234, v234
	s_nop 1
	v_mul_f32_e32 v157, v157, v233
	v_fmac_f32_e32 v157, v231, v234
	v_mul_f32_e32 v84, v84, v233
	v_fmac_f32_e32 v84, v52, v234
	v_mul_f32_e32 v85, v85, v233
	v_fmac_f32_e32 v85, v53, v234
	v_mul_f32_e32 v86, v86, v233
	v_fmac_f32_e32 v86, v54, v234
	v_mul_f32_e32 v87, v87, v233
	v_fmac_f32_e32 v87, v55, v234
	v_mul_f32_e32 v88, v88, v233
	v_fmac_f32_e32 v88, v56, v234
	v_mul_f32_e32 v89, v89, v233
	v_fmac_f32_e32 v89, v57, v234
	v_mul_f32_e32 v90, v90, v233
	v_fmac_f32_e32 v90, v58, v234
	v_mul_f32_e32 v91, v91, v233
	v_fmac_f32_e32 v91, v59, v234
	v_mul_f32_e32 v92, v92, v233
	v_fmac_f32_e32 v92, v60, v234
	v_mul_f32_e32 v93, v93, v233
	v_fmac_f32_e32 v93, v61, v234
	v_mul_f32_e32 v94, v94, v233
	v_fmac_f32_e32 v94, v62, v234
	v_mul_f32_e32 v95, v95, v233
	v_fmac_f32_e32 v95, v63, v234
	v_mul_f32_e32 v96, v96, v233
	v_fmac_f32_e32 v96, v64, v234
	v_mul_f32_e32 v97, v97, v233
	v_fmac_f32_e32 v97, v65, v234
	v_mul_f32_e32 v98, v98, v233
	v_fmac_f32_e32 v98, v66, v234
	v_mul_f32_e32 v99, v99, v233
	v_fmac_f32_e32 v99, v67, v234
	v_mov_b32_e32 v171, v232
	s_add_u32 s5, s5, 1
	s_cmp_lt_u32 s5, 6
	s_cbranch_scc1 .Lsk_merge
	s_branch .Lsk_full
